# second split-phase barrier: arrive after the fnet projection, run the ple GEMM (independent of it), wait, then the out-projection GEMM
# speedup vs baseline: 1.0135x; 1.0044x over previous
; __device__ __forceinline__ int opaque_tid() { int t = threadIdx.x; asm volatile("" : "+v"(t)); return t; }
;     __device__ __forceinline__ void init(AccMut acc, const Unit& u, int wr, int wc, int fr, int fq) const { acc_bias(acc, bias + u.pn * 256 + wc * 32 + 8 * fq); }
;     __device__ __forceinline__ void init(AccMut acc, const Unit&, int, int, int, int) const { acc_zero(acc); }
; __device__ __forceinline__ void xcd_barrier(const XcdBarrier& b) {
;     asm volatile("s_waitcnt vmcnt(0)" ::: "memory");
;     __syncthreads();
;     if (threadIdx.x == 0) {
;         unsigned long long bar_ = (unsigned long long)b.bar; unsigned bx = b.x;
;         asm volatile("" : "+s"(bar_), "+s"(bx));
;         unsigned* bar = (unsigned*)bar_;
;         __builtin_amdgcn_s_waitcnt(0);
;         unsigned nloc = b.st[0], nx = b.st[1];
;         if (nloc == 0u) { xcd_barrier_complete(bar, bx, nloc, nx); b.st[0] = nloc; b.st[1] = nx; }
;         const unsigned old = xb_add(&bar[XB_XSUB(bx)], 1u);
;         const unsigned gen = old / nloc;
;         if (old + 1u == (gen + 1u) * nloc) {
;             __builtin_amdgcn_fence(__ATOMIC_RELEASE, "agent");
;             asm volatile("s_waitcnt vmcnt(0)" ::: "memory");
;             const unsigned og = xb_add(&bar[XB_TOP], 1u);
;             const unsigned tg = og / nx;
;             if (og + 1u == (tg + 1u) * nx) xb_add(&bar[XB_TOPGEN], 1u);
;             else XB_SPIN(xb_ld(&bar[XB_TOPGEN]) == tg, bar);
;             __builtin_amdgcn_fence(__ATOMIC_ACQUIRE, "agent");
;             xb_add(&bar[XB_XGEN(bx)], 1u);
;             asm volatile("s_waitcnt vmcnt(0)" ::: "memory");
;         } else {
;             XB_SPIN(xb_ld(&bar[XB_XGEN(bx)]) == gen, bar);
;             __builtin_amdgcn_fence(__ATOMIC_ACQUIRE, "agent");
;             asm volatile("s_waitcnt vmcnt(0)" ::: "memory");
;         }
;     }
;     __syncthreads();
; __global__ void __launch_bounds__(512, 2) fwd_megakernel(Params p_) {
;     ...
;         if (PHM & 128)
;         {
;             TID_VARS
;             KARGS
;             { const int tid = opaque_tid(); pg8::Gemm g{MRG, wt + WT_OUT, M_TOK, DM, DM, DM, DM}; pg8::StaticOrder S; S.init(M_TOK, DM, G, bid);
;               EpiOut E{X, p->in[I_BOUT] + (size_t)l * DM, p->in[I_LNG] + (size_t)l * DM, XN, STATS}; pg8::gemm_phase(lds, g, S, E, tid); }
.LBB0_726:
	s_waitcnt vmcnt(0)
	s_waitcnt lgkmcnt(0)
	s_barrier
	s_mov_b64 s[40:41], exec
	v_readlane_b32 s2, v253, 5
	v_readlane_b32 s3, v253, 6
	s_and_b64 s[2:3], s[40:41], s[2:3]
	s_mov_b64 exec, s[2:3]
	s_cbranch_execz .LBB0_770
	s_add_i32 s98, s98, 1
	v_mov_b32_e32 v0, 0x20fa0
	ds_read_b64 v[2:3], v0
	v_readlane_b32 s10, v253, 2
	v_readlane_b32 s11, v253, 3
	v_readlane_b32 s12, v253, 4
	s_lshl_b32 s12, s12, 6
	s_add_i32 s12, s12, 0x3600
	s_add_u32 s14, s10, s12
	s_addc_u32 s15, s11, 0
	s_add_u32 s10, s10, 0x3b00
	s_addc_u32 s11, s11, 0
	v_mov_b64_e32 v[4:5], s[14:15]
	v_mov_b32_e32 v8, 1
	flat_atomic_add v6, v[4:5], v8 sc0
	s_waitcnt vmcnt(0) lgkmcnt(0)
	v_readfirstlane_b32 s12, v6
	v_readfirstlane_b32 s13, v2
	s_mul_i32 s13, s13, s98
	s_add_i32 s12, s12, 1
	s_cmp_lg_u32 s12, s13
	s_cbranch_scc1 .Lgb_done_6
	v_mov_b64_e32 v[4:5], s[10:11]
	buffer_wbl2 sc1
	s_waitcnt vmcnt(0) lgkmcnt(0)
	flat_atomic_add v7, v[4:5], v8 sc0
	s_waitcnt vmcnt(0) lgkmcnt(0)
.Lgb_done_6:
.LBB0_770:
	s_or_b64 exec, exec, s[40:41]
	v_readlane_b32 s4, v253, 0
	v_mov_b32_e32 v0, v246
	v_readlane_b32 s5, v253, 1
	s_waitcnt lgkmcnt(0)
	s_barrier
	s_mov_b32 s101, 1

; __device__ __forceinline__ unsigned xb_ld(unsigned* p)              { return __hip_atomic_load(p, __ATOMIC_RELAXED, __HIP_MEMORY_SCOPE_AGENT); }
; __device__ __forceinline__ unsigned xb_add(unsigned* p, unsigned v) { return __hip_atomic_fetch_add(p, v, __ATOMIC_RELAXED, __HIP_MEMORY_SCOPE_AGENT); }
; #define XB_SPIN(cond, bar) do { unsigned _sp = 0; while (cond) { __builtin_amdgcn_s_sleep(1); \
;     if ((++_sp & 255u) == 0u) { if (xb_ld(&(bar)[XB_TMO])) break; if (_sp > XB_SPIN_CAP) { atomicAdd(&(bar)[XB_TMO], 1u); break; } } } } while (0)
; __device__ __forceinline__ void xcd_barrier(const XcdBarrier& b) {
;     asm volatile("s_waitcnt vmcnt(0)" ::: "memory");
;     __syncthreads();
;     if (threadIdx.x == 0) {
;         unsigned long long bar_ = (unsigned long long)b.bar; unsigned bx = b.x;
;         asm volatile("" : "+s"(bar_), "+s"(bx));
;         unsigned* bar = (unsigned*)bar_;
;         __builtin_amdgcn_s_waitcnt(0);
;         unsigned nloc = b.st[0], nx = b.st[1];
;         if (nloc == 0u) { xcd_barrier_complete(bar, bx, nloc, nx); b.st[0] = nloc; b.st[1] = nx; }
;         const unsigned old = xb_add(&bar[XB_XSUB(bx)], 1u);
;         const unsigned gen = old / nloc;
;         if (old + 1u == (gen + 1u) * nloc) {
;             __builtin_amdgcn_fence(__ATOMIC_RELEASE, "agent");
;             asm volatile("s_waitcnt vmcnt(0)" ::: "memory");
;             const unsigned og = xb_add(&bar[XB_TOP], 1u);
;             const unsigned tg = og / nx;
;             if (og + 1u == (tg + 1u) * nx) xb_add(&bar[XB_TOPGEN], 1u);
;             else XB_SPIN(xb_ld(&bar[XB_TOPGEN]) == tg, bar);
;             __builtin_amdgcn_fence(__ATOMIC_ACQUIRE, "agent");
;             xb_add(&bar[XB_XGEN(bx)], 1u);
;             asm volatile("s_waitcnt vmcnt(0)" ::: "memory");
;         } else {
;             XB_SPIN(xb_ld(&bar[XB_XGEN(bx)]) == gen, bar);
;             __builtin_amdgcn_fence(__ATOMIC_ACQUIRE, "agent");
;             asm volatile("s_waitcnt vmcnt(0)" ::: "memory");
;         }
;     }
;     __syncthreads();
.LBB0_834:
	s_cmp_eq_u32 s101, 1
	s_cbranch_scc0 .Lp6_cont
	s_mov_b32 s101, 3
	s_waitcnt vmcnt(0)
	s_mov_b64 s[22:23], exec
	v_readlane_b32 s10, v253, 5
	v_readlane_b32 s11, v253, 6
	s_nop 0
	s_and_b64 s[10:11], s[22:23], s[10:11]
	s_mov_b64 exec, s[10:11]
	s_cbranch_execz .Lp6_wdone
	v_mov_b32_e32 v0, 0x20fa0
	ds_read_b64 v[2:3], v0
	v_readlane_b32 s10, v253, 2
	v_readlane_b32 s11, v253, 3
	s_add_u32 s10, s10, 0x3b00
	s_addc_u32 s11, s11, 0
	v_mov_b64_e32 v[4:5], s[10:11]
	s_waitcnt lgkmcnt(0)
	v_readfirstlane_b32 s14, v3
	s_mul_i32 s14, s14, s98
	s_mov_b32 s16, 0

; __device__ __forceinline__ int opaque_tid() { int t = threadIdx.x; asm volatile("" : "+v"(t)); return t; }
;     __device__ __forceinline__ void init(AccMut acc, const Unit& u, int wr, int wc, int fr, int fq) const { acc_bias(acc, bias + u.pn * 256 + wc * 32 + 8 * fq); }
;     __device__ __forceinline__ void init(AccMut acc, const Unit&, int, int, int, int) const { acc_zero(acc); }
;     __device__ __forceinline__ void init(AccMut acc, const Unit&, int, int, int, int) const { acc_zero(acc); }
;     __device__ __forceinline__ void init(AccMut acc, const Unit& u, int wr, int wc, int fr, int fq) const { acc_bias(acc, bias + u.pn * 256 + wc * 32 + 8 * fq); }
;     __device__ __forceinline__ void init(AccMut acc, const Unit&, int, int, int, int) const { acc_zero(acc); }
;     __device__ __forceinline__ void init(AccMut acc, const Unit&, int, int, int, int) const { acc_zero(acc); }
; __device__ __forceinline__ void xcd_barrier(const XcdBarrier& b) {
;     ...
;         }
;     }
;     __syncthreads();
; __global__ void __launch_bounds__(512, 2) fwd_megakernel(Params p_) {
;     ...
;             { const int tid = opaque_tid(); pg8::Gemm g{MRG, wt + WT_OUT, M_TOK, DM, DM, DM, DM}; pg8::StaticOrder S; S.init(M_TOK, DM, G, bid);
;               EpiOut E{X, p->in[I_BOUT] + (size_t)l * DM, p->in[I_LNG] + (size_t)l * DM, XN, STATS}; pg8::gemm_phase(lds, g, S, E, tid); }
.Lp6_wdone:
	s_mov_b64 exec, s[22:23]
	s_waitcnt lgkmcnt(0)
	s_barrier
	v_readlane_b32 s4, v253, 0
	v_readlane_b32 s5, v253, 1
	s_nop 3
	s_branch .Lp6_head
